# L3a queue: first two items per block assigned statically (uniform short conv items made all blocks re-contend on the counter together)
# baseline (speedup 1.0000x reference)
.LBB0_315:
	v_mov_b32_e32 v0, v172
	s_barrier
	s_nop 0
	v_cmp_eq_u32_e32 vcc, 0, v0
	s_and_saveexec_b64 s[0:1], vcc
	s_cbranch_execz .LBB0_319
	s_add_u32 s98, s8, 4
	v_cmp_eq_u32_e32 vcc, s98, v253
	s_nop 4
	s_cbranch_vccnz .Lqf_dyn_1
	s_or_b32 s99, s98, 1
	v_cmp_eq_u32_e32 vcc, s99, v253
	s_nop 4
	s_cbranch_vccnz .Lqf_st2_1
	v_mov_b32_e32 v253, s99
	v_mov_b32_e32 v0, v254
	s_branch .Lqf_wr_1
.Lqf_st2_1:
	v_mov_b32_e32 v253, s98
	v_add_u32_e32 v0, v254, v255
	s_branch .Lqf_wr_1
.Lqf_dyn_1:
	s_mov_b32 s98, 1
	s_atomic_add s98, s[8:9], 0x4 glc
	s_waitcnt lgkmcnt(0)
	v_add_u32_e32 v0, s98, v255
	v_add_u32_e32 v0, v0, v255
